# v57 + GPRO: GEMM phase prologues issue both start-up K-tiles' LDS-DMA groups before the first wait (vmcnt(8))
# baseline (speedup 1.0000x reference)
; #define PG8_STAGE(bufoff, gbase, voff) do { _Pragma("unroll") for (int _i = 0; _i < 2; ++_i) \
;         __builtin_amdgcn_global_load_lds((const unsigned*)((const char*)(gbase) + (voff)[_i]), (PG8_LAS unsigned*)(lds + (bufoff) + ldsw + _i * 8192), 16, 0, 0); } while (0)
; #define PG8_WAIT_V(n) asm volatile("s_waitcnt vmcnt(" #n ")" ::: "memory")
; #define PG8_BAR __builtin_amdgcn_s_barrier()
; template <class Epi, class Sched, bool ALIGN_EPI = false, bool SP2 = false>
; __device__ __forceinline__ void gemm_phase(PG8_LAS unsigned char* lds, const Gemm g, const Sched& S, const Epi& E) {
;     ...
;         PG8_STAGE(PG8_SB(0, 0), cB, voffB); PG8_STAGE(PG8_SB(0, 1), cB + hstep, voffB); PG8_STAGE(PG8_SA(0, 0), cA, voffA); PG8_STAGE(PG8_SA(0, 1), cA + hstep, voffA);
;         if (wr == 1) PG8_BAR;
;         PG8_WAIT_V(2); PG8_BAR;
;         PG8_STAGE(PG8_SB(1, 0), cB + kstep, voffB); PG8_STAGE(PG8_SA(1, 0), cA + kstep, voffA); PG8_STAGE(PG8_SB(1, 1), cB + hstep + kstep, voffB);
;         PG8_WAIT_V(6); PG8_BAR;
.LBB0_143:
	v_readlane_b32 s4, v254, 53
	v_mov_b32_e32 v167, v1
	v_readlane_b32 s5, v254, 54
	s_and_b32 s10, s6, 3
	s_add_i32 m0, s47, 0x18000
	v_lshl_add_u64 v[2:3], v[2:3], 0, s[72:73]
	v_lshl_add_u64 v[14:15], s[4:5], 0, v[166:167]
	v_mov_b32_e32 v165, v1
	s_lshl_b32 s84, s26, 6
	s_lshl_b32 s51, s1, 6
	s_lshl_b32 s1, s1, 13
	s_lshl_b32 s11, s10, 12
	global_load_lds_dwordx4 v[2:3], off
	v_lshl_add_u64 v[2:3], v[4:5], 0, s[72:73]
	s_add_i32 m0, s47, 0x1a000
	s_add_i32 s52, s47, 0x8000
	s_add_i32 s53, s47, 0xa000
	v_lshl_add_u64 v[16:17], s[4:5], 0, v[164:165]
	global_load_lds_dwordx4 v[2:3], off
	v_lshl_add_u64 v[2:3], v[14:15], 0, s[72:73]
	s_mov_b32 m0, s52
	s_add_u32 s6, s8, 0x40080
	global_load_lds_dwordx4 v[2:3], off
	v_lshl_add_u64 v[2:3], v[16:17], 0, s[72:73]
	s_mov_b32 m0, s53
	s_addc_u32 s7, s9, 0
	global_load_lds_dwordx4 v[2:3], off
	s_add_i32 m0, s47, 0x1c000
	v_lshl_add_u64 v[2:3], s[6:7], 0, v[0:1]
	global_load_lds_dwordx4 v[2:3], off
	v_lshl_add_u64 v[2:3], s[6:7], 0, v[162:163]
	s_add_i32 m0, s47, 0x1e000
	v_bfe_u32 v197, v6, 4, 2
	global_load_lds_dwordx4 v[2:3], off
	s_waitcnt vmcnt(8)
	s_barrier
	v_and_b32_e32 v196, 15, v6
	v_lshlrev_b32_e32 v2, 4, v197
	v_lshlrev_b32_e32 v3, 2, v6
	v_lshl_or_b32 v2, v196, 6, v2
	v_and_b32_e32 v3, 32, v3
	s_cmpk_lt_u32 s0, 0x100
	v_bitop3_b32 v4, v2, s1, v3 bitop3:0xde
	v_bitop3_b32 v204, v2, s11, v3 bitop3:0xde
	s_cselect_b64 s[60:61], -1, 0
	s_cmp_lt_u32 s10, 2
	v_lshlrev_b32_e32 v2, 14, v11
	s_cselect_b64 s[82:83], -1, 0
	s_lshl_b32 s2, s10, 6
	v_and_b32_e32 v2, 0xffff8000, v2
	s_or_b32 s54, s2, 0xfffffc00
	s_lshl_b32 s0, s10, 7
	v_readlane_b32 s1, v252, 38
	v_lshl_add_u32 v2, v10, 11, v2
	v_and_b32_e32 v3, 1, v11
	s_add_u32 s70, s1, s0
	v_lshl_or_b32 v2, v3, 6, v2
	s_addc_u32 s71, s58, 0
	v_lshl_add_u32 v168, v12, 1, v2
	v_lshlrev_b32_e32 v2, 14, v7
	s_lshl_b64 s[0:1], s[84:85], 2
	v_and_b32_e32 v2, 0xffff8000, v2
	v_writelane_b32 v253, s0, 43
	s_waitcnt vmcnt(6)
	v_lshl_add_u32 v2, v8, 11, v2
	v_and_b32_e32 v3, 1, v7
	v_writelane_b32 v253, s1, 44
	v_readlane_b32 s0, v254, 51
	v_lshl_or_b32 v2, v3, 6, v2
	v_readlane_b32 s1, v254, 52
	s_mov_b32 s3, s85
	v_mov_b32_e32 v169, v1
	v_lshl_add_u32 v170, v9, 1, v2
	v_mov_b32_e32 v171, v1
	s_mov_b32 s55, 0
	v_add_u32_e32 v205, 0, v4
	v_readlane_b32 s56, v254, 43
	s_mov_b32 s12, s0
	s_mov_b64 s[0:1], s[4:5]
	s_movk_i32 s19, 0x9a
	s_barrier
	s_branch .LBB0_146

; #define PG8_STAGE(bufoff, gbase, voff) do { _Pragma("unroll") for (int _i = 0; _i < 2; ++_i) \
;         __builtin_amdgcn_global_load_lds((const unsigned*)((const char*)(gbase) + (voff)[_i]), (PG8_LAS unsigned*)(lds + (bufoff) + ldsw + _i * 8192), 16, 0, 0); } while (0)
; #define PG8_WAIT_V(n) asm volatile("s_waitcnt vmcnt(" #n ")" ::: "memory")
; #define PG8_BAR __builtin_amdgcn_s_barrier()
; template <class Epi, class Sched, bool ALIGN_EPI = false, bool SP2 = false>
; __device__ __forceinline__ void gemm_phase(PG8_LAS unsigned char* lds, const Gemm g, const Sched& S, const Epi& E) {
;     ...
;         PG8_STAGE(PG8_SB(0, 0), cB, voffB); PG8_STAGE(PG8_SB(0, 1), cB + hstep, voffB); PG8_STAGE(PG8_SA(0, 0), cA, voffA); PG8_STAGE(PG8_SA(0, 1), cA + hstep, voffA);
;         if (wr == 1) PG8_BAR;
;         PG8_WAIT_V(2); PG8_BAR;
;         PG8_STAGE(PG8_SB(1, 0), cB + kstep, voffB); PG8_STAGE(PG8_SA(1, 0), cA + kstep, voffA); PG8_STAGE(PG8_SB(1, 1), cB + hstep + kstep, voffB);
;         PG8_WAIT_V(6); PG8_BAR;
.LBB0_866:
	s_and_b32 s22, s1, 3
	v_readlane_b32 s24, v253, 49
	s_lshl_b32 s23, s21, 13
	s_lshl_b32 s16, s22, 12
	v_readlane_b32 s25, v253, 50
	s_and_b64 s[12:13], s[24:25], exec
	v_readlane_b32 s0, v252, 8
	v_readlane_b32 s5, v252, 13
	v_readlane_b32 s0, v252, 27
	v_readlane_b32 s4, v252, 12
	s_cselect_b32 s17, s5, s0
	v_readlane_b32 s0, v252, 26
	s_cselect_b32 s19, s4, s0
	s_add_i32 m0, s45, 0x18000
	v_lshl_add_u64 v[8:9], v[8:9], 0, s[72:73]
	v_readlane_b32 s12, v252, 20
	global_load_lds_dwordx4 v[8:9], off
	v_lshl_add_u64 v[6:7], v[6:7], 0, s[72:73]
	s_add_i32 m0, s45, 0x1a000
	s_add_i32 s51, s45, 0x8000
	s_add_i32 s52, s45, 0xa000
	v_readlane_b32 s13, v252, 21
	global_load_lds_dwordx4 v[6:7], off
	v_lshl_add_u64 v[2:3], v[2:3], 0, s[72:73]
	s_mov_b32 m0, s51
	s_add_u32 s12, s36, 0x40080
	global_load_lds_dwordx4 v[2:3], off
	v_lshl_add_u64 v[2:3], v[4:5], 0, s[72:73]
	s_mov_b32 m0, s52
	s_addc_u32 s13, s37, 0
	global_load_lds_dwordx4 v[2:3], off
	s_add_i32 m0, s45, 0x1c000
	v_lshl_add_u64 v[2:3], s[12:13], 0, v[0:1]
	global_load_lds_dwordx4 v[2:3], off
	v_lshl_add_u64 v[2:3], s[12:13], 0, v[182:183]
	s_add_i32 m0, s45, 0x1e000
	s_cmpk_lt_u32 s20, 0x100
	global_load_lds_dwordx4 v[2:3], off
	s_waitcnt vmcnt(8)
	s_barrier
	v_lshrrev_b32_e32 v3, 1, v10
	v_and_b32_e32 v3, 24, v3
	v_and_b32_e32 v2, 15, v10
	v_lshlrev_b32_e32 v4, 1, v3
	v_lshl_or_b32 v204, s21, 6, v2
	v_lshl_or_b32 v2, v2, 6, v4
	v_lshlrev_b32_e32 v4, 2, v10
	v_and_b32_e32 v4, 32, v4
	v_bitop3_b32 v5, v2, s23, v4 bitop3:0xde
	v_bitop3_b32 v205, v2, s16, v4 bitop3:0xde
	v_lshlrev_b32_e32 v2, 14, v11
	v_and_b32_e32 v2, 0xffff8000, v2
	v_lshl_or_b32 v206, s22, 6, v3
	v_lshl_add_u32 v2, v12, 11, v2
	v_and_b32_e32 v3, 1, v11
	v_lshl_or_b32 v2, v3, 6, v2
	v_lshl_add_u32 v184, v13, 1, v2
	v_lshlrev_b32_e32 v2, 14, v14
	v_and_b32_e32 v2, 0xffff8000, v2
	s_waitcnt vmcnt(6)
	s_cselect_b64 s[60:61], -1, 0
	s_add_u32 s53, s19, 0xf8000000
	v_lshl_add_u32 v2, v15, 11, v2
	v_and_b32_e32 v3, 1, v14
	v_readlane_b32 s2, v252, 10
	v_readlane_b32 s3, v252, 11
	s_addc_u32 s54, s17, -1
	s_or_b64 s[68:69], s[24:25], s[90:91]
	v_lshl_or_b32 v2, v3, 6, v2
	s_xor_b64 s[16:17], s[68:69], -1
	v_mov_b32_e32 v185, v1
	v_lshl_add_u32 v186, v16, 1, v2
	v_mov_b32_e32 v187, v1
	s_mov_b32 s55, 0
	v_add_u32_e32 v207, 0, v5
	v_readlane_b32 s2, v254, 33
	v_readlane_b32 s3, v252, 47
	v_readlane_b32 s1, v252, 9
	v_readlane_b32 s6, v252, 14
	v_readlane_b32 s7, v252, 15
	v_readlane_b32 s8, v252, 16
	v_readlane_b32 s9, v252, 17
	v_readlane_b32 s10, v252, 18
	v_readlane_b32 s11, v252, 19
	v_readlane_b32 s14, v252, 22
	v_readlane_b32 s15, v252, 23
	s_barrier
	s_branch .LBB0_869

; #define PG8_STAGE(bufoff, gbase, voff) do { _Pragma("unroll") for (int _i = 0; _i < 2; ++_i) \
;         __builtin_amdgcn_global_load_lds((const unsigned*)((const char*)(gbase) + (voff)[_i]), (PG8_LAS unsigned*)(lds + (bufoff) + ldsw + _i * 8192), 16, 0, 0); } while (0)
; #define PG8_WAIT_V(n) asm volatile("s_waitcnt vmcnt(" #n ")" ::: "memory")
; #define PG8_BAR __builtin_amdgcn_s_barrier()
; template <class Epi, class Sched, bool ALIGN_EPI = false, bool SP2 = false>
; __device__ __forceinline__ void gemm_phase(PG8_LAS unsigned char* lds, const Gemm g, const Sched& S, const Epi& E) {
;     ...
;         PG8_STAGE(PG8_SB(0, 0), cB, voffB); PG8_STAGE(PG8_SB(0, 1), cB + hstep, voffB); PG8_STAGE(PG8_SA(0, 0), cA, voffA); PG8_STAGE(PG8_SA(0, 1), cA + hstep, voffA);
;         if (wr == 1) PG8_BAR;
;         PG8_WAIT_V(2); PG8_BAR;
;         PG8_STAGE(PG8_SB(1, 0), cB + kstep, voffB); PG8_STAGE(PG8_SA(1, 0), cA + kstep, voffA); PG8_STAGE(PG8_SB(1, 1), cB + hstep + kstep, voffB);
;         PG8_WAIT_V(6); PG8_BAR;
.LBB0_1029:
	v_lshl_add_u64 v[10:11], s[26:27], 0, v[0:1]
	v_mov_b32_e32 v171, v1
	v_readlane_b32 s24, v254, 59
	v_lshl_add_u64 v[12:13], s[26:27], 0, v[170:171]
	v_mov_b32_e32 v175, v1
	v_readlane_b32 s25, v254, 60
	s_and_b32 s16, s12, 3
	s_add_i32 m0, s39, 0x18000
	v_lshl_add_u64 v[10:11], v[10:11], 0, s[72:73]
	v_lshl_add_u64 v[14:15], s[24:25], 0, v[174:175]
	v_mov_b32_e32 v173, v1
	s_lshl_b32 s17, s1, 13
	s_lshl_b32 s18, s16, 12
	global_load_lds_dwordx4 v[10:11], off
	v_lshl_add_u64 v[10:11], v[12:13], 0, s[72:73]
	s_add_i32 m0, s39, 0x1a000
	s_add_i32 s49, s39, 0x8000
	s_add_i32 s50, s39, 0xa000
	v_lshl_add_u64 v[16:17], s[24:25], 0, v[172:173]
	global_load_lds_dwordx4 v[10:11], off
	v_lshl_add_u64 v[10:11], v[14:15], 0, s[72:73]
	s_mov_b32 m0, s49
	s_add_u32 s12, s26, 0x40080
	global_load_lds_dwordx4 v[10:11], off
	v_lshl_add_u64 v[10:11], v[16:17], 0, s[72:73]
	s_mov_b32 m0, s50
	s_addc_u32 s13, s27, 0
	global_load_lds_dwordx4 v[10:11], off
	s_add_i32 m0, s39, 0x1c000
	v_lshl_add_u64 v[10:11], s[12:13], 0, v[0:1]
	global_load_lds_dwordx4 v[10:11], off
	v_lshl_add_u64 v[10:11], s[12:13], 0, v[170:171]
	s_add_i32 m0, s39, 0x1e000
	v_and_b32_e32 v9, 15, v2
	global_load_lds_dwordx4 v[10:11], off
	s_waitcnt vmcnt(8)
	s_barrier
	v_lshrrev_b32_e32 v10, 1, v2
	v_and_b32_e32 v10, 24, v10
	v_lshlrev_b32_e32 v11, 1, v10
	v_lshlrev_b32_e32 v2, 2, v2
	v_lshl_or_b32 v190, s1, 6, v9
	v_lshl_or_b32 v9, v9, 6, v11
	v_and_b32_e32 v2, 32, v2
	v_bitop3_b32 v11, v9, s17, v2 bitop3:0xde
	v_bitop3_b32 v191, v9, s18, v2 bitop3:0xde
	v_lshlrev_b32_e32 v2, 14, v7
	v_and_b32_e32 v2, 0xffff8000, v2
	v_lshl_add_u32 v2, v6, 11, v2
	v_and_b32_e32 v6, 1, v7
	v_lshl_or_b32 v2, v6, 6, v2
	v_lshl_add_u32 v176, v8, 1, v2
	v_lshlrev_b32_e32 v2, 14, v3
	v_and_b32_e32 v2, 0xffff8000, v2
	s_waitcnt vmcnt(6)
	v_lshl_add_u32 v2, v4, 11, v2
	v_and_b32_e32 v3, 1, v3
	s_cmpk_lt_u32 s0, 0x100
	v_lshl_or_b32 v2, v3, 6, v2
	v_readlane_b32 s0, v255, 1
	s_cselect_b64 s[60:61], -1, 0
	v_lshl_or_b32 v192, s16, 6, v10
	v_mov_b32_e32 v177, v1
	v_lshl_add_u32 v178, v5, 1, v2
	v_mov_b32_e32 v179, v1
	s_mov_b32 s51, 0
	v_add_u32_e32 v193, 0, v11
	v_readlane_b32 s52, v254, 50
	s_mov_b32 s53, s0
	v_readlane_b32 s2, v254, 33
	v_readlane_b32 s3, v252, 47
	s_barrier
	v_readlane_b32 s1, v255, 2
	s_branch .LBB0_1032

; #define PG8_STAGE(bufoff, gbase, voff) do { _Pragma("unroll") for (int _i = 0; _i < 2; ++_i) \
;         __builtin_amdgcn_global_load_lds((const unsigned*)((const char*)(gbase) + (voff)[_i]), (PG8_LAS unsigned*)(lds + (bufoff) + ldsw + _i * 8192), 16, 0, 0); } while (0)
; #define PG8_WAIT_V(n) asm volatile("s_waitcnt vmcnt(" #n ")" ::: "memory")
; #define PG8_BAR __builtin_amdgcn_s_barrier()
; template <class Epi, class Sched, bool ALIGN_EPI = false, bool SP2 = false>
; __device__ __forceinline__ void gemm_phase(PG8_LAS unsigned char* lds, const Gemm g, const Sched& S, const Epi& E) {
;     ...
;         PG8_STAGE(PG8_SB(0, 0), cB, voffB); PG8_STAGE(PG8_SB(0, 1), cB + hstep, voffB); PG8_STAGE(PG8_SA(0, 0), cA, voffA); PG8_STAGE(PG8_SA(0, 1), cA + hstep, voffA);
;         if (wr == 1) PG8_BAR;
;         PG8_WAIT_V(2); PG8_BAR;
;         PG8_STAGE(PG8_SB(1, 0), cB + kstep, voffB); PG8_STAGE(PG8_SA(1, 0), cA + kstep, voffA); PG8_STAGE(PG8_SB(1, 1), cB + hstep + kstep, voffB);
;         PG8_WAIT_V(6); PG8_BAR;
.LBB0_1334:
	v_lshrrev_b32_e32 v18, 1, v16
	v_and_b32_e32 v18, 24, v18
	v_and_b32_e32 v17, 15, v16
	v_lshlrev_b32_e32 v19, 1, v18
	v_lshlrev_b32_e32 v16, 2, v16
	s_and_b32 s20, s18, 3
	v_lshl_or_b32 v158, s1, 6, v17
	v_lshl_or_b32 v17, v17, 6, v19
	s_lshl_b32 s1, s1, 13
	v_and_b32_e32 v16, 32, v16
	s_add_i32 m0, s29, 0x18000
	v_lshl_add_u64 v[8:9], v[8:9], 0, s[72:73]
	v_bitop3_b32 v19, v17, s1, v16 bitop3:0xde
	s_lshl_b32 s1, s20, 12
	global_load_lds_dwordx4 v[8:9], off
	v_lshl_add_u64 v[6:7], v[6:7], 0, s[72:73]
	s_add_i32 m0, s29, 0x1a000
	s_add_i32 s50, s29, 0x8000
	s_add_i32 s51, s29, 0xa000
	global_load_lds_dwordx4 v[6:7], off
	v_lshl_add_u64 v[2:3], v[2:3], 0, s[72:73]
	s_mov_b32 m0, s50
	s_add_u32 s18, s36, 0x40080
	global_load_lds_dwordx4 v[2:3], off
	v_lshl_add_u64 v[2:3], v[4:5], 0, s[72:73]
	s_mov_b32 m0, s51
	s_addc_u32 s19, s37, 0
	global_load_lds_dwordx4 v[2:3], off
	s_add_i32 m0, s29, 0x1c000
	v_lshl_add_u64 v[2:3], s[18:19], 0, v[0:1]
	global_load_lds_dwordx4 v[2:3], off
	v_lshl_add_u64 v[2:3], s[18:19], 0, v[146:147]
	s_add_i32 m0, s29, 0x1e000
	s_cmpk_lt_u32 s0, 0x100
	global_load_lds_dwordx4 v[2:3], off
	s_waitcnt vmcnt(8)
	s_barrier
	v_lshlrev_b32_e32 v2, 14, v14
	v_and_b32_e32 v2, 0xffff8000, v2
	v_lshl_add_u32 v2, v13, 11, v2
	v_and_b32_e32 v3, 1, v14
	v_lshl_or_b32 v2, v3, 6, v2
	v_lshl_add_u32 v152, v15, 1, v2
	v_lshlrev_b32_e32 v2, 14, v10
	v_and_b32_e32 v2, 0xffff8000, v2
	s_waitcnt vmcnt(6)
	v_lshl_add_u32 v2, v11, 11, v2
	v_and_b32_e32 v3, 1, v10
	v_lshl_or_b32 v2, v3, 6, v2
	v_bitop3_b32 v159, v17, s1, v16 bitop3:0xde
	s_cselect_b64 s[18:19], -1, 0
	v_lshl_or_b32 v160, s20, 6, v18
	v_mov_b32_e32 v153, v1
	v_lshl_add_u32 v154, v12, 1, v2
	v_mov_b32_e32 v155, v1
	s_mov_b32 s52, 0
	v_add_u32_e32 v161, 0, v19
	s_barrier
	s_branch .LBB0_1337

; #define PG8_STAGE(bufoff, gbase, voff) do { _Pragma("unroll") for (int _i = 0; _i < 2; ++_i) \
;         __builtin_amdgcn_global_load_lds((const unsigned*)((const char*)(gbase) + (voff)[_i]), (PG8_LAS unsigned*)(lds + (bufoff) + ldsw + _i * 8192), 16, 0, 0); } while (0)
; #define PG8_WAIT_V(n) asm volatile("s_waitcnt vmcnt(" #n ")" ::: "memory")
; #define PG8_BAR __builtin_amdgcn_s_barrier()
; template <class Epi, class Sched, bool ALIGN_EPI = false, bool SP2 = false>
; __device__ __forceinline__ void gemm_phase(PG8_LAS unsigned char* lds, const Gemm g, const Sched& S, const Epi& E) {
;     ...
;         PG8_STAGE(PG8_SB(0, 0), cB, voffB); PG8_STAGE(PG8_SB(0, 1), cB + hstep, voffB); PG8_STAGE(PG8_SA(0, 0), cA, voffA); PG8_STAGE(PG8_SA(0, 1), cA + hstep, voffA);
;         if (wr == 1) PG8_BAR;
;         PG8_WAIT_V(2); PG8_BAR;
;         PG8_STAGE(PG8_SB(1, 0), cB + kstep, voffB); PG8_STAGE(PG8_SA(1, 0), cA + kstep, voffA); PG8_STAGE(PG8_SB(1, 1), cB + hstep + kstep, voffB);
;         PG8_WAIT_V(6); PG8_BAR;
.LBB0_1408:
	v_lshrrev_b32_e32 v18, 1, v6
	v_and_b32_e32 v18, 24, v18
	v_lshl_add_u64 v[10:11], s[34:35], 0, v[0:1]
	v_mov_b32_e32 v183, v1
	v_and_b32_e32 v9, 15, v6
	v_lshlrev_b32_e32 v19, 1, v18
	v_lshlrev_b32_e32 v6, 2, v6
	v_lshl_add_u64 v[12:13], s[34:35], 0, v[182:183]
	v_mov_b32_e32 v179, v1
	s_and_b32 s17, s1, 3
	v_lshl_or_b32 v204, s0, 6, v9
	v_lshl_or_b32 v9, v9, 6, v19
	s_lshl_b32 s0, s0, 13
	v_and_b32_e32 v6, 32, v6
	s_add_i32 m0, s43, 0x18000
	v_lshl_add_u64 v[10:11], v[10:11], 0, s[72:73]
	v_lshl_add_u64 v[14:15], s[26:27], 0, v[178:179]
	v_mov_b32_e32 v181, v1
	v_bitop3_b32 v19, v9, s0, v6 bitop3:0xde
	s_lshl_b32 s0, s17, 12
	global_load_lds_dwordx4 v[10:11], off
	v_lshl_add_u64 v[10:11], v[12:13], 0, s[72:73]
	s_add_i32 m0, s43, 0x1a000
	s_add_i32 s49, s43, 0x8000
	s_add_i32 s50, s43, 0xa000
	v_lshl_add_u64 v[16:17], s[26:27], 0, v[180:181]
	v_bitop3_b32 v205, v9, s0, v6 bitop3:0xde
	global_load_lds_dwordx4 v[10:11], off
	v_lshl_add_u64 v[10:11], v[14:15], 0, s[72:73]
	s_mov_b32 m0, s49
	s_add_u32 s0, s34, 0x100080
	global_load_lds_dwordx4 v[10:11], off
	v_lshl_add_u64 v[10:11], v[16:17], 0, s[72:73]
	s_mov_b32 m0, s50
	s_addc_u32 s1, s35, 0
	global_load_lds_dwordx4 v[10:11], off
	s_add_i32 m0, s43, 0x1c000
	v_lshl_add_u64 v[10:11], s[0:1], 0, v[0:1]
	global_load_lds_dwordx4 v[10:11], off
	v_lshl_add_u64 v[10:11], s[0:1], 0, v[182:183]
	s_add_i32 m0, s43, 0x1e000
	v_lshlrev_b32_e32 v6, 16, v2
	global_load_lds_dwordx4 v[10:11], off
	s_waitcnt vmcnt(8)
	s_barrier
	v_and_b32_e32 v6, 0xfffe0000, v6
	v_lshl_add_u32 v3, v3, 13, v6
	v_and_b32_e32 v2, 1, v2
	v_lshl_or_b32 v2, v2, 6, v3
	v_lshl_add_u32 v184, v4, 1, v2
	v_lshlrev_b32_e32 v2, 16, v5
	v_and_b32_e32 v2, 0xfffe0000, v2
	s_waitcnt vmcnt(6)
	v_lshl_add_u32 v2, v7, 13, v2
	v_and_b32_e32 v3, 1, v5
	s_cmpk_lt_u32 s14, 0x100
	v_lshl_or_b32 v2, v3, 6, v2
	s_cselect_b64 s[14:15], -1, 0
	v_lshl_or_b32 v206, s17, 6, v18
	v_mov_b32_e32 v185, v1
	v_lshl_add_u32 v186, v8, 1, v2
	v_mov_b32_e32 v187, v1
	s_mov_b32 s51, 0
	v_add_u32_e32 v207, 0, v19
	s_barrier
	s_branch .LBB0_1411

; #define PG8_STAGE(bufoff, gbase, voff) do { _Pragma("unroll") for (int _i = 0; _i < 2; ++_i) \
;         __builtin_amdgcn_global_load_lds((const unsigned*)((const char*)(gbase) + (voff)[_i]), (PG8_LAS unsigned*)(lds + (bufoff) + ldsw + _i * 8192), 16, 0, 0); } while (0)
; #define PG8_WAIT_V(n) asm volatile("s_waitcnt vmcnt(" #n ")" ::: "memory")
; #define PG8_BAR __builtin_amdgcn_s_barrier()
; template <class Epi, class Sched, bool ALIGN_EPI = false, bool SP2 = false>
; __device__ __forceinline__ void gemm_phase(PG8_LAS unsigned char* lds, const Gemm g, const Sched& S, const Epi& E) {
;     ...
;         PG8_STAGE(PG8_SB(0, 0), cB, voffB); PG8_STAGE(PG8_SB(0, 1), cB + hstep, voffB); PG8_STAGE(PG8_SA(0, 0), cA, voffA); PG8_STAGE(PG8_SA(0, 1), cA + hstep, voffA);
;         if (wr == 1) PG8_BAR;
;         PG8_WAIT_V(2); PG8_BAR;
;         PG8_STAGE(PG8_SB(1, 0), cB + kstep, voffB); PG8_STAGE(PG8_SA(1, 0), cA + kstep, voffA); PG8_STAGE(PG8_SB(1, 1), cB + hstep + kstep, voffB);
;         PG8_WAIT_V(6); PG8_BAR;
.LBB0_1571:
	v_lshl_add_u64 v[10:11], s[24:25], 0, v[0:1]
	v_mov_b32_e32 v171, v1
	v_readlane_b32 s22, v255, 5
	v_lshl_add_u64 v[12:13], s[24:25], 0, v[170:171]
	v_mov_b32_e32 v175, v1
	v_readlane_b32 s23, v255, 6
	s_and_b32 s14, s10, 3
	s_add_i32 m0, s35, 0x18000
	v_lshl_add_u64 v[10:11], v[10:11], 0, s[72:73]
	v_lshl_add_u64 v[14:15], s[22:23], 0, v[174:175]
	v_mov_b32_e32 v173, v1
	s_lshl_b32 s15, s1, 13
	s_lshl_b32 s16, s14, 12
	global_load_lds_dwordx4 v[10:11], off
	v_lshl_add_u64 v[10:11], v[12:13], 0, s[72:73]
	s_add_i32 m0, s35, 0x1a000
	s_add_i32 s43, s35, 0x8000
	s_add_i32 s44, s35, 0xa000
	v_lshl_add_u64 v[16:17], s[22:23], 0, v[172:173]
	global_load_lds_dwordx4 v[10:11], off
	v_lshl_add_u64 v[10:11], v[14:15], 0, s[72:73]
	s_mov_b32 m0, s43
	s_add_u32 s10, s24, 0x100080
	global_load_lds_dwordx4 v[10:11], off
	v_lshl_add_u64 v[10:11], v[16:17], 0, s[72:73]
	s_mov_b32 m0, s44
	s_addc_u32 s11, s25, 0
	global_load_lds_dwordx4 v[10:11], off
	s_add_i32 m0, s35, 0x1c000
	v_lshl_add_u64 v[10:11], s[10:11], 0, v[0:1]
	global_load_lds_dwordx4 v[10:11], off
	v_lshl_add_u64 v[10:11], s[10:11], 0, v[170:171]
	s_add_i32 m0, s35, 0x1e000
	v_and_b32_e32 v9, 15, v3
	global_load_lds_dwordx4 v[10:11], off
	s_waitcnt vmcnt(8)
	s_barrier
	v_lshrrev_b32_e32 v10, 1, v3
	v_and_b32_e32 v10, 24, v10
	v_lshlrev_b32_e32 v11, 1, v10
	v_lshlrev_b32_e32 v3, 2, v3
	v_lshl_or_b32 v190, s1, 6, v9
	v_lshl_or_b32 v9, v9, 6, v11
	v_and_b32_e32 v3, 32, v3
	v_bitop3_b32 v11, v9, s15, v3 bitop3:0xde
	v_bitop3_b32 v191, v9, s16, v3 bitop3:0xde
	v_lshlrev_b32_e32 v3, 16, v7
	v_and_b32_e32 v3, 0xfffe0000, v3
	v_lshl_add_u32 v3, v6, 13, v3
	v_and_b32_e32 v6, 1, v7
	v_lshl_or_b32 v3, v6, 6, v3
	v_lshl_add_u32 v176, v8, 1, v3
	v_lshlrev_b32_e32 v3, 16, v2
	v_and_b32_e32 v3, 0xfffe0000, v3
	s_waitcnt vmcnt(6)
	v_lshl_add_u32 v3, v4, 13, v3
	v_and_b32_e32 v2, 1, v2
	s_cmpk_lt_u32 s0, 0x100
	v_lshl_or_b32 v2, v2, 6, v3
	v_readlane_b32 s0, v255, 1
	s_cselect_b64 s[10:11], -1, 0
	v_lshl_or_b32 v192, s14, 6, v10
	v_mov_b32_e32 v177, v1
	v_lshl_add_u32 v178, v5, 1, v2
	v_mov_b32_e32 v179, v1
	s_mov_b32 s45, 0
	v_add_u32_e32 v193, 0, v11
	v_readlane_b32 s48, v254, 50
	s_mov_b32 s49, s0
	s_barrier
	v_readlane_b32 s1, v255, 2
	s_branch .LBB0_1574
